# v53 + yt_phase: all (<=6) items' loads issued up front, items then pass through the LDS tile with no memory wait
# baseline (speedup 1.0000x reference)
; #define LAS __attribute__((address_space(3)))
; #define GAS __attribute__((address_space(1)))
; __device__ __forceinline__ void yt_phase(Frame& F, int wblk, int nblk) {
;     {
;         LAS bf16_t* LT = (LAS bf16_t*)F.lds;
;         GAS bf16_t* Yw = (GAS bf16_t*)(F.ws + WS_Y);
;         for (int it = wblk; it < 144 * 4; it += nblk) {
;             const int tile = it >> 2, c0 = (it & 3) * 128, row0 = tile * 64;
;             int t0, L; const GAS bf16_t* src;
;             if (row0 < MC) { const int sq = row0 >> 8; t0 = row0 & 255; L = CTXL; src = (const GAS bf16_t*)(F.ws + WS_YBTC) + (size_t)sq * 512 * CTXL; }
;             else { const int r = row0 - MC, sq = r >> 11; t0 = r & 2047; L = SEQ; src = (const GAS bf16_t*)(F.ws + WS_YBTL) + (size_t)sq * 512 * SEQ; }
.LBB0_1025:
	v_readlane_b32 s0, v254, 42
	v_readlane_b32 s1, v254, 43
	s_and_b64 vcc, exec, s[0:1]
	s_cbranch_vccz .LBB0_1035
	v_readlane_b32 s4, v254, 44
	v_readlane_b32 s5, v254, 45
	s_load_dwordx2 s[0:1], s[12:13], 0x130
	s_andn2_b64 vcc, exec, s[4:5]
	s_waitcnt lgkmcnt(0)
	s_cbranch_vccnz .LBB0_1034
	v_lshlrev_b32_e32 v0, 4, v184
	s_waitcnt vmcnt(0)
	v_ashrrev_i32_e32 v2, 2, v184
	v_and_b32_e32 v0, 48, v0
	s_movk_i32 s4, 0x90
	v_mul_lo_u32 v1, v2, s4
	v_lshlrev_b32_e32 v3, 1, v0
	v_add3_u32 v3, 0, v1, v3
	v_lshlrev_b32_e32 v1, 2, v184
	v_ashrrev_i32_e32 v4, 5, v184
	s_waitcnt vmcnt(22)
	v_and_b32_e32 v6, 0x7c, v1
	v_mul_u32_u24_e32 v1, 0x90, v6
	v_lshlrev_b32_e32 v5, 1, v4
	v_add3_u32 v5, 0, v1, v5
	v_lshlrev_b32_e32 v202, 1, v0
	v_lshlrev_b32_e32 v0, 1, v6
	v_readlane_b32 s4, v255, 27
	v_readlane_b32 s5, v255, 25
	v_readlane_b32 s24, v255, 23
	v_readlane_b32 s25, v255, 20
	s_mov_b32 s101, 0
	s_and_b32 s26, s5, 0x7fffffc0
	s_cmpk_gt_u32 s26, 0x3ff
	s_mov_b64 s[8:9], -1
	s_cbranch_scc0 .Lyt_h32_0
	s_add_i32 s7, s26, 0xfffffc00
	s_and_b32 s6, s7, 0x7c0
	s_lshr_b32 s7, s7, 2
	s_and_b32 s56, s7, 0x3ffffe00
	s_mov_b64 s[8:9], 0

; #define LAS __attribute__((address_space(3)))
; #define GAS __attribute__((address_space(1)))
; __device__ __forceinline__ void yt_phase(Frame& F, int wblk, int nblk) {
;     ...
;         for (int it = wblk; it < 144 * 4; it += nblk) {
;             const int tile = it >> 2, c0 = (it & 3) * 128, row0 = tile * 64;
;             int t0, L; const GAS bf16_t* src;
;             if (row0 < MC) { const int sq = row0 >> 8; t0 = row0 & 255; L = CTXL; src = (const GAS bf16_t*)(F.ws + WS_YBTC) + (size_t)sq * 512 * CTXL; }
;             else { const int r = row0 - MC, sq = r >> 11; t0 = r & 2047; L = SEQ; src = (const GAS bf16_t*)(F.ws + WS_YBTL) + (size_t)sq * 512 * SEQ; }
;             __syncthreads();
;             { const int c = F.tid >> 2, seg = F.tid & 3; const GAS bf16_t* sp = src + (size_t)(c0 + c) * L + t0 + 16 * seg;
;               *(LAS u32x4*)(LT + c * 72 + 16 * seg) = *(const GAS u32x4*)sp; *(LAS u32x4*)(LT + c * 72 + 16 * seg + 8) = *(const GAS u32x4*)(sp + 8); }
.Lyt_h29_0:
	s_and_b32 s27, s4, 0x180
	s_add_u32 s7, s0, s18
	s_addc_u32 s9, s1, s19
	s_lshl_b64 s[10:11], s[56:57], s10
	s_add_u32 s10, s7, s10
	v_add_u32_e32 v1, s27, v2
	s_addc_u32 s11, s9, s11
	v_mad_i64_i32 v[6:7], s[8:9], s8, v1, 0
	v_lshl_add_u64 v[6:7], v[6:7], 1, s[10:11]
	s_mov_b32 s7, s57
	v_lshl_add_u64 v[6:7], s[6:7], 1, v[6:7]
	v_lshl_add_u64 v[10:11], v[6:7], 0, v[202:203]
	global_load_dwordx4 v[14:17], v[10:11], off offset:16
	global_load_dwordx4 v[18:21], v[10:11], off
	v_add_u32_e32 v8, s26, v4
	v_ashrrev_i32_e32 v9, 31, v8
	v_lshlrev_b64 v[62:63], 12, v[8:9]
	s_lshl_b32 s56, s27, 1
	v_lshl_add_u64 v[62:63], s[0:1], 0, v[62:63]
	v_mov_b32_e32 v1, v203
	v_lshl_add_u64 v[62:63], v[62:63], 0, s[56:57]
	v_lshl_add_u64 v[62:63], v[62:63], 0, v[0:1]
	v_add_co_u32_e32 v62, vcc, 0x37e00000, v62
	s_nop 1
	v_addc_co_u32_e32 v63, vcc, 0, v63, vcc
	s_add_i32 s25, s25, 7
	s_addk_i32 s24, 0x70
	s_addk_i32 s5, 0x700
	s_addk_i32 s4, 0x3800
	s_add_i32 s101, s101, 1
	s_cmpk_lt_i32 s24, 0x1d0
	s_cbranch_scc0 .Lyt_go
	s_and_b32 s26, s5, 0x7fffffc0
	s_cmpk_gt_u32 s26, 0x3ff
	s_mov_b64 s[8:9], -1
	s_cbranch_scc0 .Lyt_h32_1
	s_add_i32 s7, s26, 0xfffffc00
	s_and_b32 s6, s7, 0x7c0
	s_lshr_b32 s7, s7, 2
	s_and_b32 s56, s7, 0x3ffffe00
	s_mov_b64 s[8:9], 0

; #define LAS __attribute__((address_space(3)))
; #define GAS __attribute__((address_space(1)))
; __device__ __forceinline__ void yt_phase(Frame& F, int wblk, int nblk) {
;     ...
;         for (int it = wblk; it < 144 * 4; it += nblk) {
;             const int tile = it >> 2, c0 = (it & 3) * 128, row0 = tile * 64;
;             int t0, L; const GAS bf16_t* src;
;             if (row0 < MC) { const int sq = row0 >> 8; t0 = row0 & 255; L = CTXL; src = (const GAS bf16_t*)(F.ws + WS_YBTC) + (size_t)sq * 512 * CTXL; }
;             else { const int r = row0 - MC, sq = r >> 11; t0 = r & 2047; L = SEQ; src = (const GAS bf16_t*)(F.ws + WS_YBTL) + (size_t)sq * 512 * SEQ; }
;             __syncthreads();
;             { const int c = F.tid >> 2, seg = F.tid & 3; const GAS bf16_t* sp = src + (size_t)(c0 + c) * L + t0 + 16 * seg;
;               *(LAS u32x4*)(LT + c * 72 + 16 * seg) = *(const GAS u32x4*)sp; *(LAS u32x4*)(LT + c * 72 + 16 * seg + 8) = *(const GAS u32x4*)(sp + 8); }
.Lyt_h29_1:
	s_and_b32 s27, s4, 0x180
	s_add_u32 s7, s0, s18
	s_addc_u32 s9, s1, s19
	s_lshl_b64 s[10:11], s[56:57], s10
	s_add_u32 s10, s7, s10
	v_add_u32_e32 v1, s27, v2
	s_addc_u32 s11, s9, s11
	v_mad_i64_i32 v[6:7], s[8:9], s8, v1, 0
	v_lshl_add_u64 v[6:7], v[6:7], 1, s[10:11]
	s_mov_b32 s7, s57
	v_lshl_add_u64 v[6:7], s[6:7], 1, v[6:7]
	v_lshl_add_u64 v[10:11], v[6:7], 0, v[202:203]
	global_load_dwordx4 v[22:25], v[10:11], off offset:16
	global_load_dwordx4 v[26:29], v[10:11], off
	v_add_u32_e32 v8, s26, v4
	v_ashrrev_i32_e32 v9, 31, v8
	v_lshlrev_b64 v[64:65], 12, v[8:9]
	s_lshl_b32 s56, s27, 1
	v_lshl_add_u64 v[64:65], s[0:1], 0, v[64:65]
	v_mov_b32_e32 v1, v203
	v_lshl_add_u64 v[64:65], v[64:65], 0, s[56:57]
	v_lshl_add_u64 v[64:65], v[64:65], 0, v[0:1]
	v_add_co_u32_e32 v64, vcc, 0x37e00000, v64
	s_nop 1
	v_addc_co_u32_e32 v65, vcc, 0, v65, vcc
	s_add_i32 s25, s25, 7
	s_addk_i32 s24, 0x70
	s_addk_i32 s5, 0x700
	s_addk_i32 s4, 0x3800
	s_add_i32 s101, s101, 1
	s_cmpk_lt_i32 s24, 0x1d0
	s_cbranch_scc0 .Lyt_go
	s_and_b32 s26, s5, 0x7fffffc0
	s_cmpk_gt_u32 s26, 0x3ff
	s_mov_b64 s[8:9], -1
	s_cbranch_scc0 .Lyt_h32_2
	s_add_i32 s7, s26, 0xfffffc00
	s_and_b32 s6, s7, 0x7c0
	s_lshr_b32 s7, s7, 2
	s_and_b32 s56, s7, 0x3ffffe00
	s_mov_b64 s[8:9], 0

; #define LAS __attribute__((address_space(3)))
; #define GAS __attribute__((address_space(1)))
; __device__ __forceinline__ void yt_phase(Frame& F, int wblk, int nblk) {
;     ...
;         for (int it = wblk; it < 144 * 4; it += nblk) {
;             const int tile = it >> 2, c0 = (it & 3) * 128, row0 = tile * 64;
;             int t0, L; const GAS bf16_t* src;
;             if (row0 < MC) { const int sq = row0 >> 8; t0 = row0 & 255; L = CTXL; src = (const GAS bf16_t*)(F.ws + WS_YBTC) + (size_t)sq * 512 * CTXL; }
;             else { const int r = row0 - MC, sq = r >> 11; t0 = r & 2047; L = SEQ; src = (const GAS bf16_t*)(F.ws + WS_YBTL) + (size_t)sq * 512 * SEQ; }
;             __syncthreads();
;             { const int c = F.tid >> 2, seg = F.tid & 3; const GAS bf16_t* sp = src + (size_t)(c0 + c) * L + t0 + 16 * seg;
;               *(LAS u32x4*)(LT + c * 72 + 16 * seg) = *(const GAS u32x4*)sp; *(LAS u32x4*)(LT + c * 72 + 16 * seg + 8) = *(const GAS u32x4*)(sp + 8); }
.Lyt_h29_2:
	s_and_b32 s27, s4, 0x180
	s_add_u32 s7, s0, s18
	s_addc_u32 s9, s1, s19
	s_lshl_b64 s[10:11], s[56:57], s10
	s_add_u32 s10, s7, s10
	v_add_u32_e32 v1, s27, v2
	s_addc_u32 s11, s9, s11
	v_mad_i64_i32 v[6:7], s[8:9], s8, v1, 0
	v_lshl_add_u64 v[6:7], v[6:7], 1, s[10:11]
	s_mov_b32 s7, s57
	v_lshl_add_u64 v[6:7], s[6:7], 1, v[6:7]
	v_lshl_add_u64 v[10:11], v[6:7], 0, v[202:203]
	global_load_dwordx4 v[30:33], v[10:11], off offset:16
	global_load_dwordx4 v[34:37], v[10:11], off
	v_add_u32_e32 v8, s26, v4
	v_ashrrev_i32_e32 v9, 31, v8
	v_lshlrev_b64 v[66:67], 12, v[8:9]
	s_lshl_b32 s56, s27, 1
	v_lshl_add_u64 v[66:67], s[0:1], 0, v[66:67]
	v_mov_b32_e32 v1, v203
	v_lshl_add_u64 v[66:67], v[66:67], 0, s[56:57]
	v_lshl_add_u64 v[66:67], v[66:67], 0, v[0:1]
	v_add_co_u32_e32 v66, vcc, 0x37e00000, v66
	s_nop 1
	v_addc_co_u32_e32 v67, vcc, 0, v67, vcc
	s_add_i32 s25, s25, 7
	s_addk_i32 s24, 0x70
	s_addk_i32 s5, 0x700
	s_addk_i32 s4, 0x3800
	s_add_i32 s101, s101, 1
	s_cmpk_lt_i32 s24, 0x1d0
	s_cbranch_scc0 .Lyt_go
	s_and_b32 s26, s5, 0x7fffffc0
	s_cmpk_gt_u32 s26, 0x3ff
	s_mov_b64 s[8:9], -1
	s_cbranch_scc0 .Lyt_h32_3
	s_add_i32 s7, s26, 0xfffffc00
	s_and_b32 s6, s7, 0x7c0
	s_lshr_b32 s7, s7, 2
	s_and_b32 s56, s7, 0x3ffffe00
	s_mov_b64 s[8:9], 0

; #define LAS __attribute__((address_space(3)))
; #define GAS __attribute__((address_space(1)))
; __device__ __forceinline__ void yt_phase(Frame& F, int wblk, int nblk) {
;     ...
;         for (int it = wblk; it < 144 * 4; it += nblk) {
;             const int tile = it >> 2, c0 = (it & 3) * 128, row0 = tile * 64;
;             int t0, L; const GAS bf16_t* src;
;             if (row0 < MC) { const int sq = row0 >> 8; t0 = row0 & 255; L = CTXL; src = (const GAS bf16_t*)(F.ws + WS_YBTC) + (size_t)sq * 512 * CTXL; }
;             else { const int r = row0 - MC, sq = r >> 11; t0 = r & 2047; L = SEQ; src = (const GAS bf16_t*)(F.ws + WS_YBTL) + (size_t)sq * 512 * SEQ; }
;             __syncthreads();
;             { const int c = F.tid >> 2, seg = F.tid & 3; const GAS bf16_t* sp = src + (size_t)(c0 + c) * L + t0 + 16 * seg;
;               *(LAS u32x4*)(LT + c * 72 + 16 * seg) = *(const GAS u32x4*)sp; *(LAS u32x4*)(LT + c * 72 + 16 * seg + 8) = *(const GAS u32x4*)(sp + 8); }
.Lyt_h29_3:
	s_and_b32 s27, s4, 0x180
	s_add_u32 s7, s0, s18
	s_addc_u32 s9, s1, s19
	s_lshl_b64 s[10:11], s[56:57], s10
	s_add_u32 s10, s7, s10
	v_add_u32_e32 v1, s27, v2
	s_addc_u32 s11, s9, s11
	v_mad_i64_i32 v[6:7], s[8:9], s8, v1, 0
	v_lshl_add_u64 v[6:7], v[6:7], 1, s[10:11]
	s_mov_b32 s7, s57
	v_lshl_add_u64 v[6:7], s[6:7], 1, v[6:7]
	v_lshl_add_u64 v[10:11], v[6:7], 0, v[202:203]
	global_load_dwordx4 v[38:41], v[10:11], off offset:16
	global_load_dwordx4 v[42:45], v[10:11], off
	v_add_u32_e32 v8, s26, v4
	v_ashrrev_i32_e32 v9, 31, v8
	v_lshlrev_b64 v[68:69], 12, v[8:9]
	s_lshl_b32 s56, s27, 1
	v_lshl_add_u64 v[68:69], s[0:1], 0, v[68:69]
	v_mov_b32_e32 v1, v203
	v_lshl_add_u64 v[68:69], v[68:69], 0, s[56:57]
	v_lshl_add_u64 v[68:69], v[68:69], 0, v[0:1]
	v_add_co_u32_e32 v68, vcc, 0x37e00000, v68
	s_nop 1
	v_addc_co_u32_e32 v69, vcc, 0, v69, vcc
	s_add_i32 s25, s25, 7
	s_addk_i32 s24, 0x70
	s_addk_i32 s5, 0x700
	s_addk_i32 s4, 0x3800
	s_add_i32 s101, s101, 1
	s_cmpk_lt_i32 s24, 0x1d0
	s_cbranch_scc0 .Lyt_go
	s_and_b32 s26, s5, 0x7fffffc0
	s_cmpk_gt_u32 s26, 0x3ff
	s_mov_b64 s[8:9], -1
	s_cbranch_scc0 .Lyt_h32_4
	s_add_i32 s7, s26, 0xfffffc00
	s_and_b32 s6, s7, 0x7c0
	s_lshr_b32 s7, s7, 2
	s_and_b32 s56, s7, 0x3ffffe00
	s_mov_b64 s[8:9], 0

; #define LAS __attribute__((address_space(3)))
; #define GAS __attribute__((address_space(1)))
; __device__ __forceinline__ void yt_phase(Frame& F, int wblk, int nblk) {
;     ...
;         for (int it = wblk; it < 144 * 4; it += nblk) {
;             const int tile = it >> 2, c0 = (it & 3) * 128, row0 = tile * 64;
;             int t0, L; const GAS bf16_t* src;
;             if (row0 < MC) { const int sq = row0 >> 8; t0 = row0 & 255; L = CTXL; src = (const GAS bf16_t*)(F.ws + WS_YBTC) + (size_t)sq * 512 * CTXL; }
;             else { const int r = row0 - MC, sq = r >> 11; t0 = r & 2047; L = SEQ; src = (const GAS bf16_t*)(F.ws + WS_YBTL) + (size_t)sq * 512 * SEQ; }
;             __syncthreads();
;             { const int c = F.tid >> 2, seg = F.tid & 3; const GAS bf16_t* sp = src + (size_t)(c0 + c) * L + t0 + 16 * seg;
;               *(LAS u32x4*)(LT + c * 72 + 16 * seg) = *(const GAS u32x4*)sp; *(LAS u32x4*)(LT + c * 72 + 16 * seg + 8) = *(const GAS u32x4*)(sp + 8); }
.Lyt_h29_4:
	s_and_b32 s27, s4, 0x180
	s_add_u32 s7, s0, s18
	s_addc_u32 s9, s1, s19
	s_lshl_b64 s[10:11], s[56:57], s10
	s_add_u32 s10, s7, s10
	v_add_u32_e32 v1, s27, v2
	s_addc_u32 s11, s9, s11
	v_mad_i64_i32 v[6:7], s[8:9], s8, v1, 0
	v_lshl_add_u64 v[6:7], v[6:7], 1, s[10:11]
	s_mov_b32 s7, s57
	v_lshl_add_u64 v[6:7], s[6:7], 1, v[6:7]
	v_lshl_add_u64 v[10:11], v[6:7], 0, v[202:203]
	global_load_dwordx4 v[46:49], v[10:11], off offset:16
	global_load_dwordx4 v[50:53], v[10:11], off
	v_add_u32_e32 v8, s26, v4
	v_ashrrev_i32_e32 v9, 31, v8
	v_lshlrev_b64 v[70:71], 12, v[8:9]
	s_lshl_b32 s56, s27, 1
	v_lshl_add_u64 v[70:71], s[0:1], 0, v[70:71]
	v_mov_b32_e32 v1, v203
	v_lshl_add_u64 v[70:71], v[70:71], 0, s[56:57]
	v_lshl_add_u64 v[70:71], v[70:71], 0, v[0:1]
	v_add_co_u32_e32 v70, vcc, 0x37e00000, v70
	s_nop 1
	v_addc_co_u32_e32 v71, vcc, 0, v71, vcc
	s_add_i32 s25, s25, 7
	s_addk_i32 s24, 0x70
	s_addk_i32 s5, 0x700
	s_addk_i32 s4, 0x3800
	s_add_i32 s101, s101, 1
	s_cmpk_lt_i32 s24, 0x1d0
	s_cbranch_scc0 .Lyt_go
	s_and_b32 s26, s5, 0x7fffffc0
	s_cmpk_gt_u32 s26, 0x3ff
	s_mov_b64 s[8:9], -1
	s_cbranch_scc0 .Lyt_h32_5
	s_add_i32 s7, s26, 0xfffffc00
	s_and_b32 s6, s7, 0x7c0
	s_lshr_b32 s7, s7, 2
	s_and_b32 s56, s7, 0x3ffffe00
	s_mov_b64 s[8:9], 0

; #define LAS __attribute__((address_space(3)))
; #define GAS __attribute__((address_space(1)))
; __device__ __forceinline__ void yt_phase(Frame& F, int wblk, int nblk) {
;     ...
;         for (int it = wblk; it < 144 * 4; it += nblk) {
;             const int tile = it >> 2, c0 = (it & 3) * 128, row0 = tile * 64;
;             int t0, L; const GAS bf16_t* src;
;             if (row0 < MC) { const int sq = row0 >> 8; t0 = row0 & 255; L = CTXL; src = (const GAS bf16_t*)(F.ws + WS_YBTC) + (size_t)sq * 512 * CTXL; }
;             else { const int r = row0 - MC, sq = r >> 11; t0 = r & 2047; L = SEQ; src = (const GAS bf16_t*)(F.ws + WS_YBTL) + (size_t)sq * 512 * SEQ; }
;             __syncthreads();
;             { const int c = F.tid >> 2, seg = F.tid & 3; const GAS bf16_t* sp = src + (size_t)(c0 + c) * L + t0 + 16 * seg;
;               *(LAS u32x4*)(LT + c * 72 + 16 * seg) = *(const GAS u32x4*)sp; *(LAS u32x4*)(LT + c * 72 + 16 * seg + 8) = *(const GAS u32x4*)(sp + 8); }
;             __syncthreads();
; #pragma unroll
;             for (int k = 0; k < 4; ++k) { const int tl = (F.tid >> 5) + 16 * k, c4 = (F.tid & 31) * 4;
;                 const unsigned v0 = LT[(c4 + 0) * 72 + tl], v1 = LT[(c4 + 1) * 72 + tl], v2 = LT[(c4 + 2) * 72 + tl], v3 = LT[(c4 + 3) * 72 + tl];
;                 u32x2 w; w.x = v0 | (v1 << 16); w.y = v2 | (v3 << 16);
;                 *(GAS u32x2*)(Yw + (size_t)(row0 + tl) * D + 512 + c0 + c4) = w; }
.Lyt_h29_5:
	s_and_b32 s27, s4, 0x180
	s_add_u32 s7, s0, s18
	s_addc_u32 s9, s1, s19
	s_lshl_b64 s[10:11], s[56:57], s10
	s_add_u32 s10, s7, s10
	v_add_u32_e32 v1, s27, v2
	s_addc_u32 s11, s9, s11
	v_mad_i64_i32 v[6:7], s[8:9], s8, v1, 0
	v_lshl_add_u64 v[6:7], v[6:7], 1, s[10:11]
	s_mov_b32 s7, s57
	v_lshl_add_u64 v[6:7], s[6:7], 1, v[6:7]
	v_lshl_add_u64 v[10:11], v[6:7], 0, v[202:203]
	global_load_dwordx4 v[54:57], v[10:11], off offset:16
	global_load_dwordx4 v[58:61], v[10:11], off
	v_add_u32_e32 v8, s26, v4
	v_ashrrev_i32_e32 v9, 31, v8
	v_lshlrev_b64 v[72:73], 12, v[8:9]
	s_lshl_b32 s56, s27, 1
	v_lshl_add_u64 v[72:73], s[0:1], 0, v[72:73]
	v_mov_b32_e32 v1, v203
	v_lshl_add_u64 v[72:73], v[72:73], 0, s[56:57]
	v_lshl_add_u64 v[72:73], v[72:73], 0, v[0:1]
	v_add_co_u32_e32 v72, vcc, 0x37e00000, v72
	s_nop 1
	v_addc_co_u32_e32 v73, vcc, 0, v73, vcc
	s_add_i32 s25, s25, 7
	s_addk_i32 s24, 0x70
	s_addk_i32 s5, 0x700
	s_addk_i32 s4, 0x3800
	s_add_i32 s101, s101, 1
	s_cmpk_lt_i32 s24, 0x1d0
.Lyt_go:
	s_waitcnt vmcnt(0)
	s_barrier
	ds_write_b128 v3, v[18:21]
	ds_write_b128 v3, v[14:17] offset:16
	s_waitcnt lgkmcnt(0)
	s_barrier
	ds_read_u16 v112, v5
	ds_read_u16 v113, v5 offset:144
	ds_read_u16 v114, v5 offset:288
	ds_read_u16 v115, v5 offset:432
	ds_read_u16 v116, v5 offset:32
	ds_read_u16 v117, v5 offset:176
	ds_read_u16 v118, v5 offset:320
	ds_read_u16 v119, v5 offset:464
	ds_read_u16 v120, v5 offset:64
	ds_read_u16 v121, v5 offset:208
	ds_read_u16 v122, v5 offset:352
	ds_read_u16 v123, v5 offset:496
	ds_read_u16 v124, v5 offset:96
	ds_read_u16 v125, v5 offset:240
	ds_read_u16 v126, v5 offset:384
	ds_read_u16 v127, v5 offset:528
	s_waitcnt lgkmcnt(12)
	v_lshl_or_b32 v112, v113, 16, v112
	v_lshl_or_b32 v113, v115, 16, v114
	global_store_dwordx2 v[62:63], v[112:113], off offset:1024
	s_waitcnt lgkmcnt(8)
	v_lshl_or_b32 v116, v117, 16, v116
	v_lshl_or_b32 v117, v119, 16, v118
	v_add_co_u32_e32 v92, vcc, 0x10000, v62
	s_nop 1
	v_addc_co_u32_e32 v93, vcc, 0, v63, vcc
	global_store_dwordx2 v[92:93], v[116:117], off offset:1024
	s_waitcnt lgkmcnt(4)
	v_lshl_or_b32 v120, v121, 16, v120
	v_lshl_or_b32 v121, v123, 16, v122
	v_add_co_u32_e32 v94, vcc, 0x20000, v62
	s_nop 1
	v_addc_co_u32_e32 v95, vcc, 0, v63, vcc
	global_store_dwordx2 v[94:95], v[120:121], off offset:1024
	s_waitcnt lgkmcnt(0)
	v_lshl_or_b32 v124, v125, 16, v124
	v_lshl_or_b32 v125, v127, 16, v126
	v_add_co_u32_e32 v96, vcc, 0x30000, v62
	s_nop 1
	v_addc_co_u32_e32 v97, vcc, 0, v63, vcc
	global_store_dwordx2 v[96:97], v[124:125], off offset:1024
	s_cmp_eq_u32 s101, 1
	s_cbranch_scc1 .Lyt_done
	s_barrier
	ds_write_b128 v3, v[26:29]
	ds_write_b128 v3, v[22:25] offset:16
	s_waitcnt lgkmcnt(0)
	s_barrier
	ds_read_u16 v112, v5
	ds_read_u16 v113, v5 offset:144
	ds_read_u16 v114, v5 offset:288
	ds_read_u16 v115, v5 offset:432
	ds_read_u16 v116, v5 offset:32
	ds_read_u16 v117, v5 offset:176
	ds_read_u16 v118, v5 offset:320
	ds_read_u16 v119, v5 offset:464
	ds_read_u16 v120, v5 offset:64
	ds_read_u16 v121, v5 offset:208
	ds_read_u16 v122, v5 offset:352
	ds_read_u16 v123, v5 offset:496
	ds_read_u16 v124, v5 offset:96
	ds_read_u16 v125, v5 offset:240
	ds_read_u16 v126, v5 offset:384
	ds_read_u16 v127, v5 offset:528
	s_waitcnt lgkmcnt(12)
	v_lshl_or_b32 v112, v113, 16, v112
	v_lshl_or_b32 v113, v115, 16, v114
	global_store_dwordx2 v[64:65], v[112:113], off offset:1024
	s_waitcnt lgkmcnt(8)
	v_lshl_or_b32 v116, v117, 16, v116
	v_lshl_or_b32 v117, v119, 16, v118
	v_add_co_u32_e32 v92, vcc, 0x10000, v64
	s_nop 1
	v_addc_co_u32_e32 v93, vcc, 0, v65, vcc
	global_store_dwordx2 v[92:93], v[116:117], off offset:1024
	s_waitcnt lgkmcnt(4)
	v_lshl_or_b32 v120, v121, 16, v120
	v_lshl_or_b32 v121, v123, 16, v122
	v_add_co_u32_e32 v94, vcc, 0x20000, v64
	s_nop 1
	v_addc_co_u32_e32 v95, vcc, 0, v65, vcc
	global_store_dwordx2 v[94:95], v[120:121], off offset:1024
	s_waitcnt lgkmcnt(0)
	v_lshl_or_b32 v124, v125, 16, v124
	v_lshl_or_b32 v125, v127, 16, v126
	v_add_co_u32_e32 v96, vcc, 0x30000, v64
	s_nop 1
	v_addc_co_u32_e32 v97, vcc, 0, v65, vcc
	global_store_dwordx2 v[96:97], v[124:125], off offset:1024
	s_cmp_eq_u32 s101, 2
	s_cbranch_scc1 .Lyt_done
	s_barrier
	ds_write_b128 v3, v[34:37]
	ds_write_b128 v3, v[30:33] offset:16
	s_waitcnt lgkmcnt(0)
	s_barrier
	ds_read_u16 v112, v5
	ds_read_u16 v113, v5 offset:144
	ds_read_u16 v114, v5 offset:288
	ds_read_u16 v115, v5 offset:432
	ds_read_u16 v116, v5 offset:32
	ds_read_u16 v117, v5 offset:176
	ds_read_u16 v118, v5 offset:320
	ds_read_u16 v119, v5 offset:464
	ds_read_u16 v120, v5 offset:64
	ds_read_u16 v121, v5 offset:208
	ds_read_u16 v122, v5 offset:352
	ds_read_u16 v123, v5 offset:496
	ds_read_u16 v124, v5 offset:96
	ds_read_u16 v125, v5 offset:240
	ds_read_u16 v126, v5 offset:384
	ds_read_u16 v127, v5 offset:528
	s_waitcnt lgkmcnt(12)
	v_lshl_or_b32 v112, v113, 16, v112
	v_lshl_or_b32 v113, v115, 16, v114
	global_store_dwordx2 v[66:67], v[112:113], off offset:1024
	s_waitcnt lgkmcnt(8)
	v_lshl_or_b32 v116, v117, 16, v116
	v_lshl_or_b32 v117, v119, 16, v118
	v_add_co_u32_e32 v92, vcc, 0x10000, v66
	s_nop 1
	v_addc_co_u32_e32 v93, vcc, 0, v67, vcc
	global_store_dwordx2 v[92:93], v[116:117], off offset:1024
	s_waitcnt lgkmcnt(4)
	v_lshl_or_b32 v120, v121, 16, v120
	v_lshl_or_b32 v121, v123, 16, v122
	v_add_co_u32_e32 v94, vcc, 0x20000, v66
	s_nop 1
	v_addc_co_u32_e32 v95, vcc, 0, v67, vcc
	global_store_dwordx2 v[94:95], v[120:121], off offset:1024
	s_waitcnt lgkmcnt(0)
	v_lshl_or_b32 v124, v125, 16, v124
	v_lshl_or_b32 v125, v127, 16, v126
	v_add_co_u32_e32 v96, vcc, 0x30000, v66
	s_nop 1
	v_addc_co_u32_e32 v97, vcc, 0, v67, vcc
	global_store_dwordx2 v[96:97], v[124:125], off offset:1024
	s_cmp_eq_u32 s101, 3
	s_cbranch_scc1 .Lyt_done
; #define LAS __attribute__((address_space(3)))
; #define GAS __attribute__((address_space(1)))
; __device__ __forceinline__ void yt_phase(Frame& F, int wblk, int nblk) {
;     ...
;             __syncthreads();
;             { const int c = F.tid >> 2, seg = F.tid & 3; const GAS bf16_t* sp = src + (size_t)(c0 + c) * L + t0 + 16 * seg;
;               *(LAS u32x4*)(LT + c * 72 + 16 * seg) = *(const GAS u32x4*)sp; *(LAS u32x4*)(LT + c * 72 + 16 * seg + 8) = *(const GAS u32x4*)(sp + 8); }
;             __syncthreads();
; #pragma unroll
;             for (int k = 0; k < 4; ++k) { const int tl = (F.tid >> 5) + 16 * k, c4 = (F.tid & 31) * 4;
;                 const unsigned v0 = LT[(c4 + 0) * 72 + tl], v1 = LT[(c4 + 1) * 72 + tl], v2 = LT[(c4 + 2) * 72 + tl], v3 = LT[(c4 + 3) * 72 + tl];
;                 u32x2 w; w.x = v0 | (v1 << 16); w.y = v2 | (v3 << 16);
;                 *(GAS u32x2*)(Yw + (size_t)(row0 + tl) * D + 512 + c0 + c4) = w; }
;         }
;         __syncthreads();
	s_barrier
	ds_write_b128 v3, v[42:45]
	ds_write_b128 v3, v[38:41] offset:16
	s_waitcnt lgkmcnt(0)
	s_barrier
	ds_read_u16 v112, v5
	ds_read_u16 v113, v5 offset:144
	ds_read_u16 v114, v5 offset:288
	ds_read_u16 v115, v5 offset:432
	ds_read_u16 v116, v5 offset:32
	ds_read_u16 v117, v5 offset:176
	ds_read_u16 v118, v5 offset:320
	ds_read_u16 v119, v5 offset:464
	ds_read_u16 v120, v5 offset:64
	ds_read_u16 v121, v5 offset:208
	ds_read_u16 v122, v5 offset:352
	ds_read_u16 v123, v5 offset:496
	ds_read_u16 v124, v5 offset:96
	ds_read_u16 v125, v5 offset:240
	ds_read_u16 v126, v5 offset:384
	ds_read_u16 v127, v5 offset:528
	s_waitcnt lgkmcnt(12)
	v_lshl_or_b32 v112, v113, 16, v112
	v_lshl_or_b32 v113, v115, 16, v114
	global_store_dwordx2 v[68:69], v[112:113], off offset:1024
	s_waitcnt lgkmcnt(8)
	v_lshl_or_b32 v116, v117, 16, v116
	v_lshl_or_b32 v117, v119, 16, v118
	v_add_co_u32_e32 v92, vcc, 0x10000, v68
	s_nop 1
	v_addc_co_u32_e32 v93, vcc, 0, v69, vcc
	global_store_dwordx2 v[92:93], v[116:117], off offset:1024
	s_waitcnt lgkmcnt(4)
	v_lshl_or_b32 v120, v121, 16, v120
	v_lshl_or_b32 v121, v123, 16, v122
	v_add_co_u32_e32 v94, vcc, 0x20000, v68
	s_nop 1
	v_addc_co_u32_e32 v95, vcc, 0, v69, vcc
	global_store_dwordx2 v[94:95], v[120:121], off offset:1024
	s_waitcnt lgkmcnt(0)
	v_lshl_or_b32 v124, v125, 16, v124
	v_lshl_or_b32 v125, v127, 16, v126
	v_add_co_u32_e32 v96, vcc, 0x30000, v68
	s_nop 1
	v_addc_co_u32_e32 v97, vcc, 0, v69, vcc
	global_store_dwordx2 v[96:97], v[124:125], off offset:1024
	s_cmp_eq_u32 s101, 4
	s_cbranch_scc1 .Lyt_done
	s_barrier
	ds_write_b128 v3, v[50:53]
	ds_write_b128 v3, v[46:49] offset:16
	s_waitcnt lgkmcnt(0)
	s_barrier
	ds_read_u16 v112, v5
	ds_read_u16 v113, v5 offset:144
	ds_read_u16 v114, v5 offset:288
	ds_read_u16 v115, v5 offset:432
	ds_read_u16 v116, v5 offset:32
	ds_read_u16 v117, v5 offset:176
	ds_read_u16 v118, v5 offset:320
	ds_read_u16 v119, v5 offset:464
	ds_read_u16 v120, v5 offset:64
	ds_read_u16 v121, v5 offset:208
	ds_read_u16 v122, v5 offset:352
	ds_read_u16 v123, v5 offset:496
	ds_read_u16 v124, v5 offset:96
	ds_read_u16 v125, v5 offset:240
	ds_read_u16 v126, v5 offset:384
	ds_read_u16 v127, v5 offset:528
	s_waitcnt lgkmcnt(12)
	v_lshl_or_b32 v112, v113, 16, v112
	v_lshl_or_b32 v113, v115, 16, v114
	global_store_dwordx2 v[70:71], v[112:113], off offset:1024
	s_waitcnt lgkmcnt(8)
	v_lshl_or_b32 v116, v117, 16, v116
	v_lshl_or_b32 v117, v119, 16, v118
	v_add_co_u32_e32 v92, vcc, 0x10000, v70
	s_nop 1
	v_addc_co_u32_e32 v93, vcc, 0, v71, vcc
	global_store_dwordx2 v[92:93], v[116:117], off offset:1024
	s_waitcnt lgkmcnt(4)
	v_lshl_or_b32 v120, v121, 16, v120
	v_lshl_or_b32 v121, v123, 16, v122
	v_add_co_u32_e32 v94, vcc, 0x20000, v70
	s_nop 1
	v_addc_co_u32_e32 v95, vcc, 0, v71, vcc
	global_store_dwordx2 v[94:95], v[120:121], off offset:1024
	s_waitcnt lgkmcnt(0)
	v_lshl_or_b32 v124, v125, 16, v124
	v_lshl_or_b32 v125, v127, 16, v126
	v_add_co_u32_e32 v96, vcc, 0x30000, v70
	s_nop 1
	v_addc_co_u32_e32 v97, vcc, 0, v71, vcc
	global_store_dwordx2 v[96:97], v[124:125], off offset:1024
	s_cmp_eq_u32 s101, 5
	s_cbranch_scc1 .Lyt_done
	s_barrier
	ds_write_b128 v3, v[58:61]
	ds_write_b128 v3, v[54:57] offset:16
	s_waitcnt lgkmcnt(0)
	s_barrier
	ds_read_u16 v112, v5
	ds_read_u16 v113, v5 offset:144
	ds_read_u16 v114, v5 offset:288
	ds_read_u16 v115, v5 offset:432
	ds_read_u16 v116, v5 offset:32
	ds_read_u16 v117, v5 offset:176
	ds_read_u16 v118, v5 offset:320
	ds_read_u16 v119, v5 offset:464
	ds_read_u16 v120, v5 offset:64
	ds_read_u16 v121, v5 offset:208
	ds_read_u16 v122, v5 offset:352
	ds_read_u16 v123, v5 offset:496
	ds_read_u16 v124, v5 offset:96
	ds_read_u16 v125, v5 offset:240
	ds_read_u16 v126, v5 offset:384
	ds_read_u16 v127, v5 offset:528
	s_waitcnt lgkmcnt(12)
	v_lshl_or_b32 v112, v113, 16, v112
	v_lshl_or_b32 v113, v115, 16, v114
	global_store_dwordx2 v[72:73], v[112:113], off offset:1024
	s_waitcnt lgkmcnt(8)
	v_lshl_or_b32 v116, v117, 16, v116
	v_lshl_or_b32 v117, v119, 16, v118
	v_add_co_u32_e32 v92, vcc, 0x10000, v72
	s_nop 1
	v_addc_co_u32_e32 v93, vcc, 0, v73, vcc
	global_store_dwordx2 v[92:93], v[116:117], off offset:1024
	s_waitcnt lgkmcnt(4)
	v_lshl_or_b32 v120, v121, 16, v120
	v_lshl_or_b32 v121, v123, 16, v122
	v_add_co_u32_e32 v94, vcc, 0x20000, v72
	s_nop 1
	v_addc_co_u32_e32 v95, vcc, 0, v73, vcc
	global_store_dwordx2 v[94:95], v[120:121], off offset:1024
	s_waitcnt lgkmcnt(0)
	v_lshl_or_b32 v124, v125, 16, v124
	v_lshl_or_b32 v125, v127, 16, v126
	v_add_co_u32_e32 v96, vcc, 0x30000, v72
	s_nop 1
	v_addc_co_u32_e32 v97, vcc, 0, v73, vcc
	global_store_dwordx2 v[96:97], v[124:125], off offset:1024
.Lyt_done:
	s_branch .LBB0_1034
.LBB0_1034:
	s_mov_b64 s[6:7], -1
	s_barrier
